# attention phases: one static priority raise for waves 0-3 around the unit loop
# speedup vs baseline: 1.0019x; 1.0000x over previous
.Lattn_prio_on:
	v_readfirstlane_b32 s6, v234
	s_nop 3
	s_cmpk_gt_u32 s6, 0xff
	s_cbranch_scc1 .LBB0_164
	s_setprio 1
	s_branch .LBB0_164
